# WD3: deferred weight conversions split by layer - each layer's in-proj slack converts that layer's out-proj and compress-MLP weights, layer 0's additionally converts layer 1's in-proj weights
# speedup vs baseline: 1.0008x; 1.0008x over previous
.LBB0_587:
	s_cmp_lt_u32 s50, 56
	s_cbranch_scc1 .Lwd_skip
	s_lshr_b32 s5, s52, 4
	s_lshl_b32 s5, s5, 3
	s_add_u32 s5, s5, s50
	s_sub_u32 s5, s5, 56
	s_cmp_lg_u32 s2, 0
	s_cbranch_scc1 .Lwd_done
	v_readlane_b32 s12, v234, 4
	v_readlane_b32 s13, v234, 5
	s_add_u32 s0, s80, 0x400000
	s_addc_u32 s1, s81, 0
	s_lshr_b32 s5, s52, 4
	s_lshl_b32 s5, s5, 3
	s_add_u32 s5, s5, s50
	s_sub_u32 s5, s5, 56
	s_lshl_b32 s6, s5, 8
	v_add_u32_e32 v18, s6, v156
	v_add_u32_e32 v18, 0x1f000, v18
	v_mov_b32_e32 v101, 0x8421100
	v_mov_b32_e32 v102, 0x300
	s_mov_b32 s4, 0

.Lwd_done:
	v_readlane_b32 s12, v234, 32
	v_readlane_b32 s13, v234, 33
	s_add_u32 s0, s80, 0x1400000
	s_addc_u32 s1, s81, 0
	s_lshl_b32 s6, s5, 8
	v_add_u32_e32 v18, s6, v156
	s_lshl_b32 s6, s2, 15
	v_add_u32_e32 v18, s6, v18
	v_lshrrev_b32_e32 v19, 6, v18
	v_and_b32_e32 v2, 31, v19
	v_bfe_u32 v3, v18, 3, 3
	v_lshl_or_b32 v2, v2, 3, v3
	v_lshrrev_b32_e32 v3, 5, v19
	v_and_b32_e32 v8, 7, v18
	v_lshl_or_b32 v3, v3, 3, v8
	v_lshlrev_b32_e32 v14, 15, v3
	v_lshl_or_b32 v14, v2, 4, v14
	v_lshrrev_b32_e32 v8, 7, v3
	v_lshlrev_b32_e32 v15, 21, v8
	v_lshl_or_b32 v15, v2, 13, v15
	v_and_b32_e32 v8, 0x7f, v3
	v_lshl_or_b32 v15, v8, 4, v15
	v_add_u32_e32 v16, 0x1000, v15
	global_load_dwordx4 v[20:23], v14, s[12:13]
	v_add_u32_e32 v14, 0x1000, v14
	global_load_dwordx4 v[24:27], v14, s[12:13]
	v_add_u32_e32 v14, 0x1000, v14
	global_load_dwordx4 v[28:31], v14, s[12:13]
	v_add_u32_e32 v14, 0x1000, v14
	global_load_dwordx4 v[32:35], v14, s[12:13]
	v_add_u32_e32 v14, 0x1000, v14
	global_load_dwordx4 v[36:39], v14, s[12:13]
	v_add_u32_e32 v14, 0x1000, v14
	global_load_dwordx4 v[40:43], v14, s[12:13]
	v_add_u32_e32 v14, 0x1000, v14
	global_load_dwordx4 v[44:47], v14, s[12:13]
	v_add_u32_e32 v14, 0x1000, v14
	global_load_dwordx4 v[48:51], v14, s[12:13]
	v_add_u32_e32 v11, 0x4000, v18
	v_lshrrev_b32_e32 v19, 6, v11
	v_and_b32_e32 v2, 31, v19
	v_bfe_u32 v3, v11, 3, 3
	v_lshl_or_b32 v2, v2, 3, v3
	v_lshrrev_b32_e32 v3, 5, v19
	v_and_b32_e32 v8, 7, v11
	v_lshl_or_b32 v3, v3, 3, v8
	v_lshlrev_b32_e32 v104, 15, v3
	v_lshl_or_b32 v104, v2, 4, v104
	v_lshrrev_b32_e32 v8, 7, v3
	v_lshlrev_b32_e32 v105, 21, v8
	v_lshl_or_b32 v105, v2, 13, v105
	v_and_b32_e32 v8, 0x7f, v3
	v_lshl_or_b32 v105, v8, 4, v105
	v_add_u32_e32 v106, 0x1000, v105
	global_load_dwordx4 v[52:55], v104, s[12:13]
	v_add_u32_e32 v104, 0x1000, v104
	global_load_dwordx4 v[56:59], v104, s[12:13]
	v_add_u32_e32 v104, 0x1000, v104
	global_load_dwordx4 v[60:63], v104, s[12:13]
	v_add_u32_e32 v104, 0x1000, v104
	global_load_dwordx4 v[64:67], v104, s[12:13]
	v_add_u32_e32 v104, 0x1000, v104
	global_load_dwordx4 v[68:71], v104, s[12:13]
	v_add_u32_e32 v104, 0x1000, v104
	global_load_dwordx4 v[72:75], v104, s[12:13]
	v_add_u32_e32 v104, 0x1000, v104
	global_load_dwordx4 v[76:79], v104, s[12:13]
	v_add_u32_e32 v104, 0x1000, v104
	global_load_dwordx4 v[80:83], v104, s[12:13]
	s_waitcnt vmcnt(8)
	v_cvt_pk_bf16_f32 v84, v20, v24
	v_cvt_pk_bf16_f32 v85, v28, v32
	v_cvt_pk_bf16_f32 v86, v36, v40
	v_cvt_pk_bf16_f32 v87, v44, v48
	v_cvt_pk_bf16_f32 v88, v21, v25
	v_cvt_pk_bf16_f32 v89, v29, v33
	v_cvt_pk_bf16_f32 v90, v37, v41
	v_cvt_pk_bf16_f32 v91, v45, v49
	v_cvt_pk_bf16_f32 v92, v22, v26
	v_cvt_pk_bf16_f32 v93, v30, v34
	v_cvt_pk_bf16_f32 v94, v38, v42
	v_cvt_pk_bf16_f32 v95, v46, v50
	v_cvt_pk_bf16_f32 v96, v23, v27
	v_cvt_pk_bf16_f32 v97, v31, v35
	v_cvt_pk_bf16_f32 v98, v39, v43
	v_cvt_pk_bf16_f32 v99, v47, v51
	global_store_dwordx4 v15, v[84:87], s[0:1]
	global_store_dwordx4 v15, v[88:91], s[0:1] offset:2048
	global_store_dwordx4 v16, v[92:95], s[0:1]
	global_store_dwordx4 v16, v[96:99], s[0:1] offset:2048
	s_waitcnt vmcnt(4)
	s_nop 0
	v_cvt_pk_bf16_f32 v84, v52, v56
	v_cvt_pk_bf16_f32 v85, v60, v64
	v_cvt_pk_bf16_f32 v86, v68, v72
	v_cvt_pk_bf16_f32 v87, v76, v80
	v_cvt_pk_bf16_f32 v88, v53, v57
	v_cvt_pk_bf16_f32 v89, v61, v65
	v_cvt_pk_bf16_f32 v90, v69, v73
	v_cvt_pk_bf16_f32 v91, v77, v81
	v_cvt_pk_bf16_f32 v92, v54, v58
	v_cvt_pk_bf16_f32 v93, v62, v66
	v_cvt_pk_bf16_f32 v94, v70, v74
	v_cvt_pk_bf16_f32 v95, v78, v82
	v_cvt_pk_bf16_f32 v96, v55, v59
	v_cvt_pk_bf16_f32 v97, v63, v67
	v_cvt_pk_bf16_f32 v98, v71, v75
	v_cvt_pk_bf16_f32 v99, v79, v83
	global_store_dwordx4 v105, v[84:87], s[0:1]
	global_store_dwordx4 v105, v[88:91], s[0:1] offset:2048
	global_store_dwordx4 v106, v[92:95], s[0:1]
	global_store_dwordx4 v106, v[96:99], s[0:1] offset:2048
	v_readlane_b32 s12, v234, 12
	v_readlane_b32 s13, v234, 13
	v_readlane_b32 s6, v234, 16
	v_readlane_b32 s7, v234, 17
	s_add_u32 s0, s80, 0x1800000
	s_addc_u32 s1, s81, 0
	s_lshl_b32 s8, s5, 8
	v_add_u32_e32 v18, s8, v156
	s_lshl_b32 s8, s2, 14
	v_add_u32_e32 v18, s8, v18
	v_mov_b32_e32 v108, s12
	v_mov_b32_e32 v109, s13
	v_mov_b32_e32 v110, s6
	v_mov_b32_e32 v111, s7
	v_lshrrev_b32_e32 v19, 6, v18
	v_lshrrev_b32_e32 v2, 2, v19
	v_and_b32_e32 v3, 3, v19
	v_bfe_u32 v8, v18, 3, 3
	v_lshl_or_b32 v3, v3, 3, v8
	v_and_b32_e32 v8, 31, v2
	v_and_b32_e32 v9, 7, v18
	v_lshl_or_b32 v8, v8, 3, v9
	v_lshrrev_b32_e32 v9, 5, v2
	v_lshrrev_b32_e32 v10, 1, v9
	v_lshlrev_b32_e32 v12, 20, v10
	v_lshl_or_b32 v12, v8, 12, v12
	v_lshl_or_b32 v12, v3, 4, v12
	v_mov_b32_e32 v13, 0
	v_and_b32_e32 v10, 1, v9
	v_cmp_eq_u32_e32 vcc, 1, v10
	s_nop 1
	v_cndmask_b32_e32 v14, v108, v110, vcc
	v_cndmask_b32_e32 v15, v109, v111, vcc
	v_lshl_add_u64 v[14:15], v[14:15], 0, v[12:13]
	v_lshlrev_b32_e32 v16, 19, v9
	v_lshl_or_b32 v16, v3, 14, v16
	v_lshl_or_b32 v16, v8, 4, v16
	global_load_dwordx4 v[20:23], v[14:15], off
	global_load_dwordx4 v[24:27], v[14:15], off offset:512
	global_load_dwordx4 v[28:31], v[14:15], off offset:1024
	global_load_dwordx4 v[32:35], v[14:15], off offset:1536
	global_load_dwordx4 v[36:39], v[14:15], off offset:2048
	global_load_dwordx4 v[40:43], v[14:15], off offset:2560
	global_load_dwordx4 v[44:47], v[14:15], off offset:3072
	global_load_dwordx4 v[48:51], v[14:15], off offset:3584
	s_waitcnt vmcnt(0)
	v_cvt_pk_bf16_f32 v84, v20, v24
	v_cvt_pk_bf16_f32 v85, v28, v32
	v_cvt_pk_bf16_f32 v86, v36, v40
	v_cvt_pk_bf16_f32 v87, v44, v48
	v_cvt_pk_bf16_f32 v88, v21, v25
	v_cvt_pk_bf16_f32 v89, v29, v33
	v_cvt_pk_bf16_f32 v90, v37, v41
	v_cvt_pk_bf16_f32 v91, v45, v49
	v_cvt_pk_bf16_f32 v92, v22, v26
	v_cvt_pk_bf16_f32 v93, v30, v34
	v_cvt_pk_bf16_f32 v94, v38, v42
	v_cvt_pk_bf16_f32 v95, v46, v50
	v_cvt_pk_bf16_f32 v96, v23, v27
	v_cvt_pk_bf16_f32 v97, v31, v35
	v_cvt_pk_bf16_f32 v98, v39, v43
	v_cvt_pk_bf16_f32 v99, v47, v51
	global_store_dwordx4 v16, v[84:87], s[0:1]
	v_add_u32_e32 v16, 0x1000, v16
	global_store_dwordx4 v16, v[88:91], s[0:1]
	v_add_u32_e32 v16, 0x1000, v16
	global_store_dwordx4 v16, v[92:95], s[0:1]
	v_add_u32_e32 v16, 0x1000, v16
	global_store_dwordx4 v16, v[96:99], s[0:1]
